# L2 touch-ahead prefetch (two dword loads per stage, 3 k-tiles ahead) re-enabled in FFN-up K-loop
# baseline (speedup 1.0000x reference)
; template <int EPI, int MI>
; DI void gemm_tile(const GemmDesc& g, int tm, int tn, char* smem) {
;     ...
;   const int tid = get_tid(), lane = tid & 63, wave = tid >> 6, r = lane & 31, hh = lane >> 5;
;   const int wm = wave >> 1, wn = wave & 1;
;   const int m0 = tm * BM, n0 = tn * 128;
;   const int nk = g.K >> 6;
;   f32x16 acc[MI][2];
; #pragma unroll
;   for (int a = 0; a < MI; ++a)
; #pragma unroll
;     for (int b = 0; b < 2; ++b)
; #pragma unroll
;       for (int i = 0; i < 16; ++i) acc[a][b][i] = 0.f;
;   const int srow = tid >> 3;
;   const int schunk = (tid & 7) ^ ((srow & 7) ^ ((srow >> 3) & 3));
;     ...
;   const int rowA = wm * (32 * MI) + r, rowB = wn * 64 + r;
;   const int hk = hh ^ ((r & 7) ^ ((r >> 3) & 3));
;     ...
;   G_GLDS(0, 0);
;   asm volatile("s_waitcnt vmcnt(0)" ::: "memory");
;   __syncthreads();
; template <int EPI, int MI>
; DI void gemm_phase(const GemmDesc& g, char* smem, int vb, int nvb) {
;     ...
;   for (int q = start; q < local; q += step) {
;     const int mg = q / per;
;     const int rem = q - mg * per;
;     const int tn = rem / PM;
;     const int tm = mbase + mg * PM + (rem - tn * PM);
.LBB0_202:
	s_abs_i32 s1, s5
	v_readlane_b32 s15, v219, 45
	s_mul_hi_u32 s15, s1, s15
	v_readlane_b32 s18, v219, 44
	s_mul_i32 s16, s15, s18
	s_sub_i32 s1, s1, s16
	s_ashr_i32 s0, s5, 31
	s_add_i32 s16, s15, 1
	s_sub_i32 s17, s1, s18
	s_cmp_ge_u32 s1, s18
	s_cselect_b32 s15, s16, s15
	s_cselect_b32 s1, s17, s1
	s_add_i32 s16, s15, 1
	s_cmp_ge_u32 s1, s18
	s_cselect_b32 s1, s16, s15
	s_xor_b32 s1, s1, s0
	s_sub_i32 s15, s1, s0
	s_mul_i32 s16, s15, s18
	s_sub_i32 s16, s5, s16
	s_abs_i32 s18, s16
	v_readlane_b32 s19, v219, 46
	s_mul_hi_u32 s19, s18, s19
	v_readlane_b32 s42, v218, 32
	s_mul_i32 s38, s19, s42
	s_sub_i32 s18, s18, s38
	s_ashr_i32 s17, s16, 31
	s_add_i32 s38, s19, 1
	s_sub_i32 s39, s18, s42
	s_cmp_ge_u32 s18, s42
	s_cselect_b32 s19, s38, s19
	s_cselect_b32 s18, s39, s18
	s_add_i32 s38, s19, 1
	s_cmp_ge_u32 s18, s42
	s_cselect_b32 s18, s38, s19
	s_xor_b32 s18, s18, s17
	s_sub_i32 s39, s18, s17
	s_sub_i32 s15, s15, s39
	v_mov_b32_e32 v4, v132
	s_mul_i32 s15, s15, s42
	s_add_i32 s16, s16, s54
	s_add_i32 s38, s16, s15
	v_ashrrev_i32_e32 v97, 3, v4
	v_ashrrev_i32_e32 v120, 7, v4
	v_bfe_u32 v0, v4, 6, 2
	v_xor_b32_e32 v1, v97, v4
	s_mulk_i32 s38, 0xc0
	v_and_b32_e32 v121, 31, v4
	v_bitop3_b32 v2, v1, v0, 7 bitop3:0x6c
	v_mul_lo_u32 v0, v120, s6
	v_and_b32_e32 v115, 7, v4
	v_or_b32_e32 v5, v0, v121
	v_lshrrev_b32_e32 v0, 3, v4
	s_waitcnt vmcnt(10)
	v_add_u32_e32 v98, s38, v97
	v_bfe_u32 v122, v4, 5, 1
	v_bitop3_b32 v0, v0, v115, 3 bitop3:0x6c
	v_ashrrev_i32_e32 v99, 31, v98
	v_xor_b32_e32 v6, v0, v122
	v_lshlrev_b64 v[0:1], 11, v[98:99]
	v_readlane_b32 s42, v223, 59
	v_lshlrev_b32_e32 v99, 4, v4
	v_readlane_b32 s43, v223, 60
	v_lshlrev_b32_e32 v100, 4, v2
	v_lshl_add_u32 v2, s39, 7, v97
	v_add_u32_e32 v124, 0, v99
	v_lshl_add_u64 v[0:1], s[42:43], 0, v[0:1]
	v_mov_b32_e32 v101, v96
	v_ashrrev_i32_e32 v3, 31, v2
	v_readfirstlane_b32 s15, v124
	v_add_u32_e32 v125, 0x1000, v124
	v_lshl_add_u64 v[0:1], v[0:1], 0, v[100:101]
	v_lshlrev_b64 v[2:3], 11, v[2:3]
	s_mov_b32 m0, s15
	s_mov_b64 s[42:43], 0x10000
	v_readfirstlane_b32 s15, v125
	v_add_u32_e32 v126, 0x2000, v124
	s_waitcnt vmcnt(9)
	v_lshl_add_u64 v[102:103], s[70:71], 0, v[2:3]
	global_load_lds_dwordx4 v[0:1], off
	v_lshl_add_u64 v[2:3], v[0:1], 0, s[42:43]
	s_mov_b32 m0, s15
	s_mov_b64 s[44:45], 0x20000
	v_readfirstlane_b32 s15, v126
	v_add_u32_e32 v127, 0x3000, v124
	global_load_lds_dwordx4 v[2:3], off
	v_lshl_add_u64 v[2:3], v[0:1], 0, s[44:45]
	s_mov_b32 m0, s15
	s_mov_b64 s[46:47], 0x30000
	v_readfirstlane_b32 s15, v127
	v_add_u32_e32 v128, 0x4000, v124
	global_load_lds_dwordx4 v[2:3], off
	v_lshl_add_u64 v[2:3], v[0:1], 0, s[46:47]
	s_mov_b32 m0, s15
	s_mov_b64 s[52:53], 0x40000
	v_readfirstlane_b32 s15, v128
	v_add_u32_e32 v129, 0x5000, v124
	global_load_lds_dwordx4 v[2:3], off
	v_lshl_add_u64 v[2:3], v[0:1], 0, s[52:53]
	s_mov_b32 m0, s15
	s_mov_b64 s[52:53], 0x50000
	v_readfirstlane_b32 s15, v129
	v_add_u32_e32 v130, 0xc000, v124
	global_load_lds_dwordx4 v[2:3], off
	v_lshl_add_u64 v[0:1], v[0:1], 0, s[52:53]
	s_mov_b32 m0, s15
	v_readfirstlane_b32 s15, v130
	v_add_u32_e32 v131, 0xd000, v124
	global_load_lds_dwordx4 v[0:1], off
	v_lshl_add_u64 v[0:1], v[102:103], 0, v[100:101]
	s_mov_b32 m0, s15
	v_readfirstlane_b32 s15, v131
	v_add_u32_e32 v153, 0xe000, v124
	global_load_lds_dwordx4 v[0:1], off
	v_lshl_add_u64 v[2:3], v[0:1], 0, s[42:43]
	s_mov_b32 m0, s15
	v_readfirstlane_b32 s15, v153
	v_add_u32_e32 v154, 0xf000, v124
	global_load_lds_dwordx4 v[2:3], off
	v_lshl_add_u64 v[2:3], v[0:1], 0, s[44:45]
	s_mov_b32 m0, s15
	v_readfirstlane_b32 s15, v154
	global_load_lds_dwordx4 v[2:3], off
	v_lshl_add_u64 v[0:1], v[0:1], 0, s[46:47]
	s_mov_b32 m0, s15
	s_mul_i32 s0, s0, 43
	global_load_lds_dwordx4 v[0:1], off
	s_add_i32 s17, s17, s0
	s_sub_i32 s0, s17, s18
	s_mul_i32 s1, s1, 43
	s_sub_i32 s0, s0, s1
	v_readlane_b32 s1, v218, 33
	v_bfe_u32 v123, v4, 6, 1
	v_lshlrev_b32_e32 v0, 7, v121
	s_mul_i32 s0, s1, s0
	v_lshl_or_b32 v0, v123, 13, v0
	s_add_i32 s0, s0, s4
	v_add_u32_e32 v156, 0, v0
	v_add_u32_e32 v158, s10, v0
	v_add_u32_e32 v0, s0, v97
	v_ashrrev_i32_e32 v1, 31, v0
	s_waitcnt vmcnt(0)
	v_lshlrev_b64 v[0:1], 11, v[0:1]
	v_lshlrev_b32_e32 v157, 4, v6
	v_lshl_add_u64 v[104:105], s[70:71], 0, v[0:1]
	v_mov_b32_e32 v0, 0
	v_lshl_add_u32 v155, v5, 7, 0
	s_mov_b32 s15, 0
	v_mov_b32_e32 v1, v0
	v_mov_b32_e32 v2, v0
	v_mov_b32_e32 v3, v0
	v_mov_b32_e32 v4, v0
	v_mov_b32_e32 v5, v0
	v_mov_b32_e32 v6, v0
	v_mov_b32_e32 v7, v0
	v_mov_b32_e32 v8, v0
	v_mov_b32_e32 v9, v0
	v_mov_b32_e32 v10, v0
	v_mov_b32_e32 v11, v0
	v_mov_b32_e32 v12, v0
	v_mov_b32_e32 v13, v0
	v_mov_b32_e32 v14, v0
	v_mov_b32_e32 v15, v0
	v_mov_b32_e32 v16, v0
	v_mov_b32_e32 v17, v0
	v_mov_b32_e32 v18, v0
	v_mov_b32_e32 v19, v0
	v_mov_b32_e32 v20, v0
	v_mov_b32_e32 v21, v0
	v_mov_b32_e32 v22, v0
	v_mov_b32_e32 v23, v0
	v_mov_b32_e32 v24, v0
	v_mov_b32_e32 v25, v0
	v_mov_b32_e32 v26, v0
	v_mov_b32_e32 v27, v0
	v_mov_b32_e32 v28, v0
	v_mov_b32_e32 v29, v0
	v_mov_b32_e32 v30, v0
	v_mov_b32_e32 v31, v0
	v_mov_b32_e32 v32, v0
	v_mov_b32_e32 v33, v0
	v_mov_b32_e32 v34, v0
	v_mov_b32_e32 v35, v0
	v_mov_b32_e32 v36, v0
	v_mov_b32_e32 v37, v0
	v_mov_b32_e32 v38, v0
	v_mov_b32_e32 v39, v0
	v_mov_b32_e32 v40, v0
	v_mov_b32_e32 v41, v0
	v_mov_b32_e32 v42, v0
	v_mov_b32_e32 v43, v0
	v_mov_b32_e32 v44, v0
	v_mov_b32_e32 v45, v0
	v_mov_b32_e32 v46, v0
	v_mov_b32_e32 v47, v0
	v_mov_b32_e32 v48, v0
	s_waitcnt vmcnt(0)
; template <int EPI, int MI>
; DI void gemm_tile(const GemmDesc& g, int tm, int tn, char* smem) {
;     ...
;   G_GLDS(0, 0);
;   asm volatile("s_waitcnt vmcnt(0)" ::: "memory");
;   __syncthreads();
;   for (int kt = 0; kt < nk; kt += 2) {
;     if (kt + 1 < nk) G_GLDS(kt + 1, 1);
;     G_COMPUTE(0);
;     asm volatile("s_waitcnt vmcnt(0)" ::: "memory");
;     __syncthreads();
;     if (kt + 1 < nk) {
;       if (kt + 2 < nk) G_GLDS(kt + 2, 0);
;       G_COMPUTE(1);
;       asm volatile("s_waitcnt vmcnt(0)" ::: "memory");
;       __syncthreads();
;     }
;   }
	v_mov_b32_e32 v49, v0
	v_mov_b32_e32 v50, v0
	v_mov_b32_e32 v51, v0
	v_mov_b32_e32 v52, v0
	v_mov_b32_e32 v53, v0
	v_mov_b32_e32 v54, v0
	v_mov_b32_e32 v55, v0
	v_mov_b32_e32 v56, v0
	v_mov_b32_e32 v57, v0
	v_mov_b32_e32 v58, v0
	v_mov_b32_e32 v59, v0
	v_mov_b32_e32 v60, v0
	v_mov_b32_e32 v61, v0
	v_mov_b32_e32 v62, v0
	v_mov_b32_e32 v63, v0
	v_mov_b32_e32 v64, v0
	v_mov_b32_e32 v65, v0
	v_mov_b32_e32 v66, v0
	v_mov_b32_e32 v67, v0
	v_mov_b32_e32 v68, v0
	v_mov_b32_e32 v69, v0
	v_mov_b32_e32 v70, v0
	v_mov_b32_e32 v71, v0
	v_mov_b32_e32 v72, v0
	v_mov_b32_e32 v73, v0
	v_mov_b32_e32 v74, v0
	v_mov_b32_e32 v75, v0
	v_mov_b32_e32 v76, v0
	v_mov_b32_e32 v77, v0
	v_mov_b32_e32 v78, v0
	v_mov_b32_e32 v79, v0
	v_mov_b32_e32 v80, v0
	v_mov_b32_e32 v81, v0
	v_mov_b32_e32 v82, v0
	v_mov_b32_e32 v83, v0
	v_mov_b32_e32 v84, v0
	v_mov_b32_e32 v85, v0
	v_mov_b32_e32 v86, v0
	v_mov_b32_e32 v87, v0
	v_mov_b32_e32 v88, v0
	v_mov_b32_e32 v89, v0
	v_mov_b32_e32 v90, v0
	v_mov_b32_e32 v91, v0
	v_mov_b32_e32 v92, v0
	v_mov_b32_e32 v93, v0
	v_mov_b32_e32 v94, v0
	v_mov_b32_e32 v95, v0
	v_xor_b32_e32 v159, 32, v157
	v_xor_b32_e32 v160, 64, v157
	v_xor_b32_e32 v161, 0x60, v157
	s_mov_b64 s[18:19], 0x80
	s_mov_b64 s[42:43], 0x10080
	v_add_u32_e32 v162, v155, v157
	v_add_u32_e32 v163, v155, v159
	v_add_u32_e32 v164, v155, v160
	v_add_u32_e32 v165, v155, v161
	v_add_u32_e32 v166, v156, v157
	v_add_u32_e32 v167, v156, v159
	v_add_u32_e32 v168, v156, v160
	v_add_u32_e32 v169, v156, v161
	v_add_u32_e32 v170, v158, v157
	v_add_u32_e32 v171, v158, v159
	v_add_u32_e32 v172, v158, v160
	v_add_u32_e32 v173, v158, v161
	v_lshl_add_u64 v[174:175], v[104:105], 0, v[100:101]
	v_lshl_add_u64 v[176:177], v[102:103], 0, v[100:101]
	v_readfirstlane_b32 s100, v124
	s_movk_i32 s16, 0xc0
	v_cmp_gt_u32_e32 vcc, s16, v132
	v_add_u32_e32 v106, s38, v132
	s_lshl_b32 s17, s39, 7
	s_sub_u32 s16, s17, s16
	v_add_u32_e32 v107, s16, v132
	v_cndmask_b32_e32 v106, v107, v106, vcc
	v_lshlrev_b32_e32 v106, 11, v106
	v_mov_b32_e32 v107, 0x3472000
	v_cndmask_b32_e32 v107, 0, v107, vcc
	v_add_u32_e32 v106, v106, v107
	v_mov_b32_e32 v107, 0
	v_lshl_add_u64 v[252:253], s[70:71], 0, v[106:107]
	v_lshrrev_b32_e32 v106, 2, v132
	s_add_u32 s17, s17, 64
	v_add_u32_e32 v106, s17, v106
	v_lshlrev_b32_e32 v106, 11, v106
	v_lshl_add_u64 v[108:109], s[70:71], 0, v[106:107]
	global_load_dword v254, v[252:253], off offset:128
	global_load_dword v254, v[108:109], off offset:128
	global_load_dword v254, v[252:253], off offset:256
	global_load_dword v254, v[108:109], off offset:256
	s_waitcnt vmcnt(4) lgkmcnt(0)
	s_barrier
	s_add_u32 m0, s100, 0x6000
	v_lshl_add_u64 v[106:107], v[174:175], 0, s[96:97]
	global_load_lds_dwordx4 v[106:107], off
	s_add_u32 m0, s100, 0x7000
	v_lshl_add_u64 v[106:107], v[174:175], 0, s[50:51]
	global_load_lds_dwordx4 v[106:107], off
	ds_read_b128 v[236:239], v166 offset:49152
	ds_read_b128 v[240:243], v166 offset:53248
	ds_read_b128 v[224:227], v162
	ds_read_b128 v[228:231], v162 offset:4096
	s_mov_b32 s15, 0
.Lga_loop:
	ds_read_b128 v[232:235], v162 offset:8192
	s_waitcnt lgkmcnt(2)
	v_mfma_f32_32x32x16_bf16 v[80:95], v[224:227], v[236:239], v[80:95]
	v_mfma_f32_32x32x16_bf16 v[64:79], v[224:227], v[240:243], v[64:79]
	s_add_u32 m0, s100, 0x8000
	v_lshl_add_u64 v[106:107], v[174:175], 0, s[24:25]
	global_load_lds_dwordx4 v[106:107], off
	s_add_u32 m0, s100, 0x9000
	v_lshl_add_u64 v[106:107], v[174:175], 0, s[26:27]
	global_load_lds_dwordx4 v[106:107], off
	ds_read_b128 v[244:247], v167 offset:49152
	ds_read_b128 v[248:251], v167 offset:53248
	ds_read_b128 v[224:227], v163
	s_waitcnt lgkmcnt(4)
	v_mfma_f32_32x32x16_bf16 v[48:63], v[228:231], v[236:239], v[48:63]
	v_mfma_f32_32x32x16_bf16 v[32:47], v[228:231], v[240:243], v[32:47]
	s_add_u32 m0, s100, 0xa000
	v_lshl_add_u64 v[106:107], v[174:175], 0, s[28:29]
	global_load_lds_dwordx4 v[106:107], off
	s_add_u32 m0, s100, 0xb000
	v_lshl_add_u64 v[106:107], v[174:175], 0, s[30:31]
	global_load_lds_dwordx4 v[106:107], off
	v_lshl_add_u64 v[174:175], v[174:175], 0, s[18:19]
	ds_read_b128 v[228:231], v163 offset:4096
	s_waitcnt lgkmcnt(4)
	v_mfma_f32_32x32x16_bf16 v[16:31], v[232:235], v[236:239], v[16:31]
	v_mfma_f32_32x32x16_bf16 v[0:15], v[232:235], v[240:243], v[0:15]
	s_add_u32 m0, s100, 0x10000
	v_lshl_add_u64 v[106:107], v[176:177], 0, s[18:19]
	global_load_lds_dwordx4 v[106:107], off
	s_add_u32 m0, s100, 0x11000
	v_lshl_add_u64 v[106:107], v[176:177], 0, s[42:43]
	global_load_lds_dwordx4 v[106:107], off
	ds_read_b128 v[232:235], v163 offset:8192
	s_waitcnt lgkmcnt(2)
	v_mfma_f32_32x32x16_bf16 v[80:95], v[224:227], v[244:247], v[80:95]
	v_mfma_f32_32x32x16_bf16 v[64:79], v[224:227], v[248:251], v[64:79]
	s_mov_b64 s[16:17], 0x20080
	s_add_u32 m0, s100, 0x12000
	v_lshl_add_u64 v[106:107], v[176:177], 0, s[16:17]
	global_load_lds_dwordx4 v[106:107], off
	s_mov_b64 s[16:17], 0x30080
	s_add_u32 m0, s100, 0x13000
	v_lshl_add_u64 v[106:107], v[176:177], 0, s[16:17]
	global_load_lds_dwordx4 v[106:107], off
	v_lshl_add_u64 v[176:177], v[176:177], 0, s[18:19]
	ds_read_b128 v[236:239], v168 offset:49152
	ds_read_b128 v[240:243], v168 offset:53248
	ds_read_b128 v[224:227], v164
	s_waitcnt lgkmcnt(4)
	v_mfma_f32_32x32x16_bf16 v[48:63], v[228:231], v[244:247], v[48:63]
	v_mfma_f32_32x32x16_bf16 v[32:47], v[228:231], v[248:251], v[32:47]
	ds_read_b128 v[228:231], v164 offset:4096
	s_waitcnt lgkmcnt(4)
	v_mfma_f32_32x32x16_bf16 v[16:31], v[232:235], v[244:247], v[16:31]
	v_mfma_f32_32x32x16_bf16 v[0:15], v[232:235], v[248:251], v[0:15]
	ds_read_b128 v[232:235], v164 offset:8192
	s_waitcnt lgkmcnt(2)
	v_mfma_f32_32x32x16_bf16 v[80:95], v[224:227], v[236:239], v[80:95]
	v_mfma_f32_32x32x16_bf16 v[64:79], v[224:227], v[240:243], v[64:79]
	ds_read_b128 v[244:247], v169 offset:49152
	ds_read_b128 v[248:251], v169 offset:53248
	ds_read_b128 v[224:227], v165
	s_waitcnt lgkmcnt(4)
	v_mfma_f32_32x32x16_bf16 v[48:63], v[228:231], v[236:239], v[48:63]
	v_mfma_f32_32x32x16_bf16 v[32:47], v[228:231], v[240:243], v[32:47]
	ds_read_b128 v[228:231], v165 offset:4096
	s_waitcnt lgkmcnt(4)
	v_mfma_f32_32x32x16_bf16 v[16:31], v[232:235], v[236:239], v[16:31]
	v_mfma_f32_32x32x16_bf16 v[0:15], v[232:235], v[240:243], v[0:15]
	ds_read_b128 v[232:235], v165 offset:8192
	s_waitcnt lgkmcnt(2)
	v_mfma_f32_32x32x16_bf16 v[80:95], v[224:227], v[244:247], v[80:95]
	v_mfma_f32_32x32x16_bf16 v[64:79], v[224:227], v[248:251], v[64:79]
	global_load_dword v254, v[252:253], off offset:384
	global_load_dword v254, v[108:109], off offset:384
	v_lshl_add_u64 v[252:253], v[252:253], 0, s[18:19]
	v_lshl_add_u64 v[108:109], v[108:109], 0, s[18:19]
	s_waitcnt lgkmcnt(0)
	s_waitcnt vmcnt(2)
	s_barrier
	s_cmp_eq_u32 s15, 14
	s_cbranch_scc1 .Lga_noearly
	s_mov_b32 m0, s100
	v_lshl_add_u64 v[106:107], v[174:175], 0, s[96:97]
	global_load_lds_dwordx4 v[106:107], off
	s_add_u32 m0, s100, 0x1000
	v_lshl_add_u64 v[106:107], v[174:175], 0, s[50:51]
	global_load_lds_dwordx4 v[106:107], off
; template <int EPI, int MI>
; DI void gemm_tile(const GemmDesc& g, int tm, int tn, char* smem) {
;     ...
;   G_GLDS(0, 0);
;   asm volatile("s_waitcnt vmcnt(0)" ::: "memory");
;   __syncthreads();
;   for (int kt = 0; kt < nk; kt += 2) {
;     if (kt + 1 < nk) G_GLDS(kt + 1, 1);
;     G_COMPUTE(0);
;     asm volatile("s_waitcnt vmcnt(0)" ::: "memory");
;     __syncthreads();
;     if (kt + 1 < nk) {
;       if (kt + 2 < nk) G_GLDS(kt + 2, 0);
;       G_COMPUTE(1);
;       asm volatile("s_waitcnt vmcnt(0)" ::: "memory");
;       __syncthreads();
;     }
;   }
.Lga_noearly:
	ds_read_b128 v[236:239], v170
	ds_read_b128 v[240:243], v170 offset:4096
	ds_read_b128 v[224:227], v162 offset:24576
	v_mfma_f32_32x32x16_bf16 v[48:63], v[228:231], v[244:247], v[48:63]
	v_mfma_f32_32x32x16_bf16 v[32:47], v[228:231], v[248:251], v[32:47]
	ds_read_b128 v[228:231], v162 offset:28672
	v_mfma_f32_32x32x16_bf16 v[16:31], v[232:235], v[244:247], v[16:31]
	v_mfma_f32_32x32x16_bf16 v[0:15], v[232:235], v[248:251], v[0:15]
	s_cmp_eq_u32 s15, 14
	s_cbranch_scc1 .Lga_last
	ds_read_b128 v[232:235], v162 offset:32768
	s_waitcnt lgkmcnt(2)
	v_mfma_f32_32x32x16_bf16 v[80:95], v[224:227], v[236:239], v[80:95]
	v_mfma_f32_32x32x16_bf16 v[64:79], v[224:227], v[240:243], v[64:79]
	s_add_u32 m0, s100, 0x2000
	v_lshl_add_u64 v[106:107], v[174:175], 0, s[24:25]
	global_load_lds_dwordx4 v[106:107], off
	s_add_u32 m0, s100, 0x3000
	v_lshl_add_u64 v[106:107], v[174:175], 0, s[26:27]
	global_load_lds_dwordx4 v[106:107], off
	ds_read_b128 v[244:247], v171
	ds_read_b128 v[248:251], v171 offset:4096
	ds_read_b128 v[224:227], v163 offset:24576
	s_waitcnt lgkmcnt(4)
	v_mfma_f32_32x32x16_bf16 v[48:63], v[228:231], v[236:239], v[48:63]
	v_mfma_f32_32x32x16_bf16 v[32:47], v[228:231], v[240:243], v[32:47]
	s_add_u32 m0, s100, 0x4000
	v_lshl_add_u64 v[106:107], v[174:175], 0, s[28:29]
	global_load_lds_dwordx4 v[106:107], off
	s_add_u32 m0, s100, 0x5000
	v_lshl_add_u64 v[106:107], v[174:175], 0, s[30:31]
	global_load_lds_dwordx4 v[106:107], off
	v_lshl_add_u64 v[174:175], v[174:175], 0, s[18:19]
	ds_read_b128 v[228:231], v163 offset:28672
	s_waitcnt lgkmcnt(4)
	v_mfma_f32_32x32x16_bf16 v[16:31], v[232:235], v[236:239], v[16:31]
	v_mfma_f32_32x32x16_bf16 v[0:15], v[232:235], v[240:243], v[0:15]
	s_add_u32 m0, s100, 0xc000
	v_lshl_add_u64 v[106:107], v[176:177], 0, s[18:19]
	global_load_lds_dwordx4 v[106:107], off
	s_add_u32 m0, s100, 0xd000
	v_lshl_add_u64 v[106:107], v[176:177], 0, s[42:43]
	global_load_lds_dwordx4 v[106:107], off
	ds_read_b128 v[232:235], v163 offset:32768
	s_waitcnt lgkmcnt(2)
	v_mfma_f32_32x32x16_bf16 v[80:95], v[224:227], v[244:247], v[80:95]
	v_mfma_f32_32x32x16_bf16 v[64:79], v[224:227], v[248:251], v[64:79]
	s_mov_b64 s[16:17], 0x20080
	s_add_u32 m0, s100, 0xe000
	v_lshl_add_u64 v[106:107], v[176:177], 0, s[16:17]
	global_load_lds_dwordx4 v[106:107], off
	s_mov_b64 s[16:17], 0x30080
	s_add_u32 m0, s100, 0xf000
	v_lshl_add_u64 v[106:107], v[176:177], 0, s[16:17]
	global_load_lds_dwordx4 v[106:107], off
	v_lshl_add_u64 v[176:177], v[176:177], 0, s[18:19]
	ds_read_b128 v[236:239], v172
	ds_read_b128 v[240:243], v172 offset:4096
	ds_read_b128 v[224:227], v164 offset:24576
	s_waitcnt lgkmcnt(4)
	v_mfma_f32_32x32x16_bf16 v[48:63], v[228:231], v[244:247], v[48:63]
	v_mfma_f32_32x32x16_bf16 v[32:47], v[228:231], v[248:251], v[32:47]
	ds_read_b128 v[228:231], v164 offset:28672
	s_waitcnt lgkmcnt(4)
	v_mfma_f32_32x32x16_bf16 v[16:31], v[232:235], v[244:247], v[16:31]
	v_mfma_f32_32x32x16_bf16 v[0:15], v[232:235], v[248:251], v[0:15]
	ds_read_b128 v[232:235], v164 offset:32768
	s_waitcnt lgkmcnt(2)
	v_mfma_f32_32x32x16_bf16 v[80:95], v[224:227], v[236:239], v[80:95]
	v_mfma_f32_32x32x16_bf16 v[64:79], v[224:227], v[240:243], v[64:79]
	ds_read_b128 v[244:247], v173
	ds_read_b128 v[248:251], v173 offset:4096
	ds_read_b128 v[224:227], v165 offset:24576
	s_waitcnt lgkmcnt(4)
	v_mfma_f32_32x32x16_bf16 v[48:63], v[228:231], v[236:239], v[48:63]
	v_mfma_f32_32x32x16_bf16 v[32:47], v[228:231], v[240:243], v[32:47]
	ds_read_b128 v[228:231], v165 offset:28672
	s_waitcnt lgkmcnt(4)
	v_mfma_f32_32x32x16_bf16 v[16:31], v[232:235], v[236:239], v[16:31]
	v_mfma_f32_32x32x16_bf16 v[0:15], v[232:235], v[240:243], v[0:15]
	ds_read_b128 v[232:235], v165 offset:32768
	s_waitcnt lgkmcnt(2)
	v_mfma_f32_32x32x16_bf16 v[80:95], v[224:227], v[244:247], v[80:95]
	v_mfma_f32_32x32x16_bf16 v[64:79], v[224:227], v[248:251], v[64:79]
	global_load_dword v254, v[252:253], off offset:384
	global_load_dword v254, v[108:109], off offset:384
	v_lshl_add_u64 v[252:253], v[252:253], 0, s[18:19]
	v_lshl_add_u64 v[108:109], v[108:109], 0, s[18:19]
	s_waitcnt lgkmcnt(0)
	s_waitcnt vmcnt(2)
	s_barrier
	s_add_u32 m0, s100, 0x6000
	v_lshl_add_u64 v[106:107], v[174:175], 0, s[96:97]
	global_load_lds_dwordx4 v[106:107], off
	s_add_u32 m0, s100, 0x7000
	v_lshl_add_u64 v[106:107], v[174:175], 0, s[50:51]
	global_load_lds_dwordx4 v[106:107], off
	ds_read_b128 v[236:239], v166 offset:49152
	ds_read_b128 v[240:243], v166 offset:53248
	ds_read_b128 v[224:227], v162
	v_mfma_f32_32x32x16_bf16 v[48:63], v[228:231], v[244:247], v[48:63]
	v_mfma_f32_32x32x16_bf16 v[32:47], v[228:231], v[248:251], v[32:47]
	ds_read_b128 v[228:231], v162 offset:4096
	v_mfma_f32_32x32x16_bf16 v[16:31], v[232:235], v[244:247], v[16:31]
	v_mfma_f32_32x32x16_bf16 v[0:15], v[232:235], v[248:251], v[0:15]
	s_add_u32 s15, s15, 2
	s_branch .Lga_loop
